# v20 + attention work-item prologue: tab, 4 Q fragment loads and first K/V stage loads issued up front with counted vmcnt (were serialized load-wait-reduce)
# baseline (speedup 1.0000x reference)
.LBB0_134:
	s_and_b32 s11, s40, 7
	s_and_saveexec_b64 s[6:7], s[42:43]
	s_cbranch_execz .LBB0_136
	s_mul_i32 s8, s11, 0x84
	v_add_u32_e32 v2, s8, v133
	v_ashrrev_i32_e32 v3, 31, v2
	v_lshl_add_u64 v[2:3], v[2:3], 2, s[2:3]
	global_load_dword v68, v[2:3], off
.LBB0_136:
	s_or_b64 exec, exec, s[6:7]
	s_ashr_i32 s7, s40, 4
	s_lshr_b32 s8, s40, 4
	s_bfe_u32 s6, s40, 0x40003
	s_and_b32 s7, s7, -16
	s_and_b32 s8, s8, 8
	s_or_b32 s16, s7, s8
	s_and_b32 s7, s40, 0x100
	s_xor_b32 s8, s6, 15
	s_cmp_eq_u32 s7, 0
	s_cselect_b32 s10, s6, s8
	v_lshl_add_u32 v163, s10, 7, v193
	s_lshl_b32 s12, s16, 8
	v_or_b32_e32 v207, v163, v189
	s_ashr_i32 s13, s12, 31
	v_add_u32_e32 v2, s12, v207
	s_lshl_b64 s[6:7], s[12:13], 11
	v_ashrrev_i32_e32 v3, 31, v2
	s_add_u32 s6, s15, s6
	v_lshlrev_b64 v[2:3], 11, v[2:3]
	s_addc_u32 s7, s21, s7
	s_lshl_b32 s86, s11, 8
	v_lshl_add_u64 v[2:3], s[4:5], 0, v[2:3]
	v_lshl_add_u64 v[164:165], v[2:3], 0, s[86:87]
	v_lshlrev_b32_e32 v0, 1, v132
	v_lshl_add_u64 v[2:3], v[164:165], 0, v[0:1]
	global_load_dwordx4 v[4:7], v[2:3], off
	global_load_dwordx4 v[8:11], v[2:3], off offset:64
	global_load_dwordx4 v[12:15], v[2:3], off offset:128
	global_load_dwordx4 v[16:19], v[2:3], off offset:192
	s_add_u32 s8, s6, s86
	s_addc_u32 s9, s7, 0
	s_or_b32 s6, s16, s11
	s_ashr_i32 s7, s6, 31
	s_lshl_b64 s[6:7], s[6:7], 19
	s_add_u32 s6, s25, s6
	v_mov_b32_e32 v159, v1
	s_addc_u32 s7, s30, s7
	v_lshl_add_u64 v[166:167], s[8:9], 0, v[158:159]
	v_mov_b32_e32 v161, v1
	v_lshl_add_u64 v[168:169], s[6:7], 0, v[160:161]
	v_lshl_add_u64 v[48:49], s[6:7], 0, v[148:149]
	v_lshl_add_u64 v[44:45], v[166:167], 0, v[152:153]
	v_lshl_add_u64 v[52:53], v[48:49], 0, v[160:161]
	global_load_dwordx4 v[44:47], v[44:45], off
	global_load_dwordx4 v[48:51], v[52:53], off offset:128
	v_lshl_add_u64 v[2:3], v[166:167], 0, v[140:141]
	global_load_dwordx4 v[20:23], v[2:3], off
	v_lshl_add_u64 v[2:3], v[168:169], 0, v[142:143]
	global_load_dwordx4 v[24:27], v[2:3], off
	v_lshl_add_u64 v[2:3], v[166:167], 0, v[146:147]
	global_load_dwordx4 v[28:31], v[2:3], off
	v_lshl_add_u64 v[2:3], v[168:169], 0, v[148:149]
	global_load_dwordx4 v[40:43], v[2:3], off
	v_lshl_add_u64 v[2:3], v[166:167], 0, v[150:151]
	global_load_dwordx4 v[32:35], v[2:3], off
	v_lshl_add_u64 v[2:3], s[6:7], 0, v[142:143]
	v_lshl_add_u64 v[2:3], v[2:3], 0, v[160:161]
	global_load_dwordx4 v[36:39], v[2:3], off offset:128
	s_and_saveexec_b64 s[6:7], s[42:43]
	s_cbranch_execz .Latt_tab_done
	s_waitcnt vmcnt(12)
	ds_write_b32 v194, v68
.Latt_tab_done:
	s_or_b64 exec, exec, s[6:7]
	s_waitcnt vmcnt(11)
	v_and_b32_e32 v60, 0xffff0000, v4
	v_mul_f32_e32 v61, v60, v60
	v_lshlrev_b32_e32 v60, 16, v4
	v_fmac_f32_e32 v61, v60, v60
	v_lshlrev_b32_e32 v60, 16, v5
	v_fmac_f32_e32 v61, v60, v60
	v_and_b32_e32 v60, 0xffff0000, v5
	v_fmac_f32_e32 v61, v60, v60
	v_lshlrev_b32_e32 v60, 16, v6
	v_fmac_f32_e32 v61, v60, v60
	v_and_b32_e32 v60, 0xffff0000, v6
	v_fmac_f32_e32 v61, v60, v60
	v_lshlrev_b32_e32 v60, 16, v7
	v_fmac_f32_e32 v61, v60, v60
	v_and_b32_e32 v60, 0xffff0000, v7
	v_fmac_f32_e32 v61, v60, v60
	s_waitcnt vmcnt(10)
	v_and_b32_e32 v60, 0xffff0000, v8
	v_mul_f32_e32 v62, v60, v60
	v_lshlrev_b32_e32 v60, 16, v8
	v_fmac_f32_e32 v62, v60, v60
	v_lshlrev_b32_e32 v60, 16, v9
	v_fmac_f32_e32 v62, v60, v60
	v_and_b32_e32 v60, 0xffff0000, v9
	v_fmac_f32_e32 v62, v60, v60
	v_lshlrev_b32_e32 v60, 16, v10
	v_fmac_f32_e32 v62, v60, v60
	v_and_b32_e32 v60, 0xffff0000, v10
	v_fmac_f32_e32 v62, v60, v60
	v_lshlrev_b32_e32 v60, 16, v11
	v_fmac_f32_e32 v62, v60, v60
	v_and_b32_e32 v60, 0xffff0000, v11
	v_fmac_f32_e32 v62, v60, v60
	v_add_f32_e32 v0, v61, v62
	ds_bpermute_b32 v61, v195, v0
	s_waitcnt lgkmcnt(0)
	v_add_f32_e32 v0, v0, v61
	ds_bpermute_b32 v54, v196, v0
	s_waitcnt vmcnt(9)
	v_and_b32_e32 v63, 0xffff0000, v12
	v_mul_f32_e32 v65, v63, v63
	v_lshlrev_b32_e32 v63, 16, v12
	v_fmac_f32_e32 v65, v63, v63
	v_lshlrev_b32_e32 v63, 16, v13
	v_fmac_f32_e32 v65, v63, v63
	v_and_b32_e32 v63, 0xffff0000, v13
	v_fmac_f32_e32 v65, v63, v63
	v_lshlrev_b32_e32 v63, 16, v14
	v_fmac_f32_e32 v65, v63, v63
	v_and_b32_e32 v63, 0xffff0000, v14
	v_fmac_f32_e32 v65, v63, v63
	v_lshlrev_b32_e32 v63, 16, v15
	v_fmac_f32_e32 v65, v63, v63
	v_and_b32_e32 v63, 0xffff0000, v15
	v_fmac_f32_e32 v65, v63, v63
	s_waitcnt vmcnt(8)
	v_and_b32_e32 v66, 0xffff0000, v16
	v_mul_f32_e32 v67, v66, v66
	v_lshlrev_b32_e32 v66, 16, v16
	v_fmac_f32_e32 v67, v66, v66
	v_lshlrev_b32_e32 v66, 16, v17
	v_fmac_f32_e32 v67, v66, v66
	v_and_b32_e32 v66, 0xffff0000, v17
	v_fmac_f32_e32 v67, v66, v66
	v_lshlrev_b32_e32 v66, 16, v18
	v_fmac_f32_e32 v67, v66, v66
	v_and_b32_e32 v66, 0xffff0000, v18
	v_fmac_f32_e32 v67, v66, v66
	v_lshlrev_b32_e32 v66, 16, v19
	v_fmac_f32_e32 v67, v66, v66
	v_and_b32_e32 v66, 0xffff0000, v19
	v_fmac_f32_e32 v67, v66, v66
	v_add_f32_e32 v66, v65, v67
	ds_bpermute_b32 v67, v195, v66
	s_waitcnt lgkmcnt(0)
	v_add_f32_e32 v55, v66, v67
	ds_bpermute_b32 v56, v196, v55
	s_waitcnt vmcnt(5)
	ds_write_b128 v203, v[20:23] offset:1024
	s_waitcnt vmcnt(4)
	ds_write_b128 v204, v[24:27] offset:18432
	s_waitcnt vmcnt(3)
	ds_write_b128 v205, v[28:31] offset:1024
	s_waitcnt vmcnt(2)
	ds_write_b128 v206, v[40:43] offset:18432
	s_cmp_eq_u32 s10, 0
	s_cbranch_scc1 .LBB0_138
	v_lshl_add_u64 v[24:25], v[166:167], 0, v[156:157]
	v_lshl_add_u64 v[20:21], v[166:167], 0, v[154:155]
	global_load_dwordx4 v[20:23], v[20:21], off
	s_nop 0
	global_load_dwordx4 v[28:31], v[24:25], off
	s_nop 0
	global_load_dwordx4 v[24:27], v[2:3], off offset:256
	global_load_dwordx4 v[40:43], v[52:53], off offset:256
